# k_rope items: two per CU, the last 64 items on the 24 CUs that own only five GEMM tiles of the phase
# baseline (speedup 1.0000x reference)
; #define LAS __attribute__((address_space(3)))
; DI void krope_phase(const Frame& F, int crank, int ncu) {
;     const bf16_t* H = (const bf16_t*)(F.ws + WS_HB); const bf16_t* Wk = (const bf16_t*)(F.ws + WS_W + W_KR); bf16_t* KR = (bf16_t*)(F.ws + WS_KR);
;     const float* rm = (const float*)(F.ws + WS_ROPEM);
;     const int r32 = F.lane & 31, h5 = F.lane >> 5, w = F.wave;
;     LAS float* part = (LAS float*)F.lds;
;     for (int it = crank; it < MT / 32; it += ncu) {
; DI void phase_g1(const Frame& F) {
;     const unsigned char* W = F.ws + WS_W; const char* H = (const char*)(F.ws + WS_HB);
;     pg8::Sched2 S; S.tileBytes = 256L * 1024 * 2; S.G = F.G; S.c = F.bid;
;     S.j0 = pg8::JobD{H, (const char*)(W + W_IN), MT / 256, NIN / 256, 1, 0, 0};
;     S.j1 = pg8::JobD{(const char*)(W + W_T), H, 4, MT / 256, 1, 0, 0};
;     S.n0 = (MT / 256) * (NIN / 256); S.total = S.n0 + 4 * (MT / 256);
;     krope_phase(F, F.bid, F.G);
.LBB0_537:
	s_andn2_b64 vcc, exec, s[60:61]
	s_cbranch_vccnz .LBB0_662
	s_cmpk_gt_u32 s96, 0x23f
	s_cbranch_scc1 .LBB0_575
	v_lshrrev_b32_e32 v0, 5, v186
	s_add_u32 s6, s94, 0x200000
	v_lshlrev_b32_e32 v96, 3, v0
	v_lshlrev_b32_e32 v0, 4, v0
	v_mov_b32_e32 v1, v97
	v_readlane_b32 s4, v255, 31
	s_addc_u32 s7, s95, 0
	v_lshl_add_u64 v[2:3], s[94:95], 0, v[0:1]
	s_lshl_b32 s16, s4, 8
	v_and_b32_e32 v4, 31, v225
	v_lshl_add_u64 v[2:3], v[2:3], 0, s[16:17]
	s_mov_b64 s[2:3], 0x3e00000
	v_lshl_add_u64 v[16:17], v[2:3], 0, s[2:3]
	v_lshlrev_b32_e32 v2, 11, v4
	v_mov_b32_e32 v3, v97
	v_lshl_add_u64 v[2:3], s[94:95], 0, v[2:3]
	v_lshl_add_u64 v[0:1], v[2:3], 0, v[0:1]
	v_lshl_add_u64 v[0:1], v[0:1], 0, s[16:17]
	s_mov_b64 s[2:3], 0x1d80000
	v_lshl_add_u64 v[18:19], v[0:1], 0, s[2:3]
	s_lshl_b32 s2, s4, 12
	v_lshl_add_u64 v[0:1], s[94:95], 0, v[96:97]
	s_mov_b64 s[4:5], 0x8f00000
	s_add_i32 s10, s2, 0
	v_readlane_b32 s2, v255, 32
	v_lshl_add_u64 v[20:21], v[0:1], 0, s[4:5]
	v_lshlrev_b32_e32 v0, 2, v186
	s_cmp_lt_u32 s2, 64
	v_add_u32_e32 v22, s10, v0
	v_add_u32_e32 v23, 0, v0
	v_xor_b32_e32 v24, 0x80, v0
	v_lshlrev_b32_e32 v0, 5, v4
	s_cselect_b64 s[8:9], -1, 0
	v_cmp_gt_u32_e64 s[2:3], 32, v186
	v_lshl_or_b32 v96, s96, 5, v4
	s_lshl_b32 s12, s93, 5
	v_lshl_or_b32 v25, s96, 10, v0
	s_lshl_b32 s13, s93, 10
	s_mov_b32 s14, s96
	s_mov_b32 s19, s93
	s_movk_i32 s18, 0x240
	s_cmp_lt_u32 s96, 232
	s_cselect_b32 s18, 0x200, s18
	global_load_dwordx4 v[100:103], v[18:19], off
	global_load_dwordx4 v[104:107], v[18:19], off offset:32
	global_load_dwordx4 v[108:111], v[18:19], off offset:64
	global_load_dwordx4 v[112:115], v[18:19], off offset:96
	global_load_dwordx4 v[116:119], v[18:19], off offset:128
	global_load_dwordx4 v[120:123], v[18:19], off offset:160
	global_load_dwordx4 v[124:127], v[18:19], off offset:192
	global_load_dwordx4 v[128:131], v[18:19], off offset:224
	v_lshlrev_b64 v[4:5], 11, v[96:97]
	v_lshl_add_u64 v[38:39], v[16:17], 0, v[4:5]
	global_load_dwordx4 v[132:135], v[38:39], off
	global_load_dwordx4 v[136:139], v[38:39], off offset:32
	global_load_dwordx4 v[140:143], v[38:39], off offset:64
	global_load_dwordx4 v[144:147], v[38:39], off offset:96
	global_load_dwordx4 v[148:151], v[38:39], off offset:128
	global_load_dwordx4 v[152:155], v[38:39], off offset:160
	global_load_dwordx4 v[156:159], v[38:39], off offset:192
	global_load_dwordx4 v[160:163], v[38:39], off offset:224
	s_branch .LBB0_542

; DI void krope_phase(const Frame& F, int crank, int ncu) {
;     ...
;     for (int it = crank; it < MT / 32; it += ncu) {
.LBB0_541:
	s_add_i32 s14, s14, s19
	v_add_u32_e32 v96, s12, v96
	s_cmp_lt_u32 s14, s18
	v_add_u32_e32 v25, s13, v25
	s_cbranch_scc0 .LBB0_575
	s_cmp_lt_u32 s96, 232
	s_cbranch_scc1 .LBB0_542
	s_movk_i32 s19, 24
	s_movk_i32 s12, 0x300
	s_movk_i32 s13, 0x6000
.LBB0_542:
	s_add_i32 s15, s14, s19
	s_cmp_lt_u32 s15, s18
	s_cbranch_scc0 .Lkr_np
	v_add_u32_e32 v84, s12, v96
	v_mov_b32_e32 v85, v97
	v_lshlrev_b64 v[86:87], 11, v[84:85]
	v_lshl_add_u64 v[88:89], v[16:17], 0, v[86:87]
	global_load_dwordx4 v[188:191], v[88:89], off
	global_load_dwordx4 v[192:195], v[88:89], off offset:32
	global_load_dwordx4 v[196:199], v[88:89], off offset:64
	global_load_dwordx4 v[200:203], v[88:89], off offset:96
	global_load_dwordx4 v[204:207], v[88:89], off offset:128
	global_load_dwordx4 v[208:211], v[88:89], off offset:160
	global_load_dwordx4 v[228:231], v[88:89], off offset:192
	global_load_dwordx4 v[232:235], v[88:89], off offset:224
	s_waitcnt vmcnt(8)
	s_branch .Lkr_go
